# plus: rmsnorm-row jobs (both copies) keep their 12 loop-invariant norm-weight/shift/scale vectors in registers instead of reloading and waiting 4x per row
# speedup vs baseline: 1.0441x; 1.0049x over previous
; __device__ __forceinline__ void norm_job(const Params& p, int l, int job, bool from_x) {
;     ...
;   const int rowbase0 = job * 64 + wid * 16;
;   const float* src0;
;   if (from_x) src0 = rowbase0 < MLAT ? p.x + (size_t)rowbase0 * 1024 : p.ctx + (size_t)(rowbase0 - MLAT) * 1024;
;   else src0 = (const float*)(ws + OFF_XNEW) + (size_t)rowbase0 * 1024;
;   float4 nx0, nx1, nx2, nx3;
;   nx0 = *(const float4*)&src0[lane * 4]; nx1 = *(const float4*)&src0[lane * 4 + 256];
;   nx2 = *(const float4*)&src0[lane * 4 + 512]; nx3 = *(const float4*)&src0[lane * 4 + 768];
;   for (int i = 0; i < 16; ++i) {
;     int row = rowbase0 + i;
;     int v = row < MLAT ? (row >> 13) : 2;
;     const float* mods = (const float*)(ws + OFF_MODS) + (l * 3 + v) * 6144;
;     float4 xv[4];
;     xv[0] = nx0; xv[1] = nx1; xv[2] = nx2; xv[3] = nx3;
;     if (i + 1 < 16) {
;       const float* sn = src0 + (size_t)(i + 1) * 1024;
;       nx0 = *(const float4*)&sn[lane * 4]; nx1 = *(const float4*)&sn[lane * 4 + 256];
;       nx2 = *(const float4*)&sn[lane * 4 + 512]; nx3 = *(const float4*)&sn[lane * 4 + 768];
;     }
;     float ss = 0.f;
; #pragma unroll
;     for (int q = 0; q < 4; ++q) {
;       ss += xv[q].x * xv[q].x + xv[q].y * xv[q].y + xv[q].z * xv[q].z + xv[q].w * xv[q].w;
;     }
;     ss = wave_sum(ss);
;     float rstd = rsqrtf(ss * (1.f / 1024.f) + EPSF);
;     if (from_x) {
;       float* dstr = (float*)(ws + OFF_XNEW) + (size_t)row * 1024;
; #pragma unroll
;       for (int q = 0; q < 4; ++q) *(float4*)&dstr[lane * 4 + 256 * q] = xv[q];
;     } else if (row < MLAT) {
;       float* dstr = p.out + (size_t)row * 1024;
; #pragma unroll
;       for (int q = 0; q < 4; ++q) *(float4*)&dstr[lane * 4 + 256 * q] = xv[q];
;     }
; #pragma unroll
;     for (int q = 0; q < 4; ++q) {
;       int col = lane * 4 + 256 * q;
;       float4 w = *(const float4*)&nw[col];
;       float4 sh = *(const float4*)&mods[col];
;       float4 sc = *(const float4*)&mods[1024 + col];
.LBB0_169:
	s_and_b64 vcc, exec, s[0:1]
	s_cbranch_vccz .LBB0_156
	v_mov_b32_e32 v4, v172
	v_readlane_b32 s0, v239, 7
	v_ashrrev_i32_e32 v0, 2, v4
	v_and_b32_e32 v5, -16, v0
	s_waitcnt vmcnt(0)
	v_lshl_add_u32 v50, s60, 6, v5
	v_ashrrev_i32_e32 v0, 31, v50
	v_add_u32_e32 v2, 0xffffc000, v50
	v_cmp_gt_i32_e32 vcc, s84, v50
	v_readlane_b32 s1, v239, 8
	v_readlane_b32 s5, v239, 12
	v_cndmask_b32_e32 v1, 0, v0, vcc
	v_cndmask_b32_e32 v0, v2, v50, vcc
	v_readlane_b32 s4, v239, 11
	v_mov_b32_e32 v2, s5
	v_mov_b32_e32 v3, s1
	v_cndmask_b32_e32 v3, v2, v3, vcc
	v_mov_b32_e32 v2, s4
	v_mov_b32_e32 v6, s0
	v_cndmask_b32_e32 v2, v2, v6, vcc
	v_lshlrev_b64 v[0:1], 12, v[0:1]
	v_lshl_add_u64 v[0:1], v[2:3], 0, v[0:1]
	v_lshlrev_b32_e32 v2, 2, v4
	v_readlane_b32 s52, v239, 59
	v_and_b32_e32 v30, 0xfc, v2
	v_readlane_b32 s54, v239, 61
	v_readlane_b32 s55, v239, 62
	v_lshlrev_b32_e32 v64, 2, v30
	s_mov_b64 s[16:17], s[54:55]
	s_mov_b32 s48, 0
	v_lshl_add_u64 v[32:33], v[0:1], 0, v[64:65]
	global_load_dwordx4 v[12:15], v[32:33], off
	global_load_dwordx4 v[8:11], v[32:33], off offset:1024
	global_load_dwordx4 v[0:3], v[32:33], off offset:2048
	global_load_dwordx4 v[16:19], v[32:33], off offset:3072
	v_and_b32_e32 v4, 64, v173
	v_add_u32_e32 v4, 64, v4
	v_xor_b32_e32 v6, 32, v173
	v_cmp_lt_i32_e32 vcc, v6, v4
	s_add_u32 s0, s16, 0x1b2d6100
	s_addc_u32 s1, s17, 0
	v_cndmask_b32_e32 v6, v173, v6, vcc
	v_lshlrev_b32_e32 v31, 2, v6
	v_xor_b32_e32 v6, 16, v173
	v_cmp_lt_i32_e32 vcc, v6, v4
	s_lshl_b32 s4, s48, 10
	s_ashr_i32 s5, s4, 31
	v_cndmask_b32_e32 v6, v173, v6, vcc
	v_lshlrev_b32_e32 v44, 2, v6
	v_xor_b32_e32 v6, 8, v173
	v_cmp_lt_i32_e32 vcc, v6, v4
	v_readlane_b32 s12, v239, 19
	s_lshl_b64 s[4:5], s[4:5], 2
	v_cndmask_b32_e32 v6, v173, v6, vcc
	v_lshlrev_b32_e32 v45, 2, v6
	v_xor_b32_e32 v6, 4, v173
	v_cmp_lt_i32_e32 vcc, v6, v4
	v_readlane_b32 s13, v239, 20
	s_add_u32 s54, s12, s4
	v_cndmask_b32_e32 v6, v173, v6, vcc
	s_addc_u32 s55, s13, s5
	v_lshlrev_b32_e32 v46, 2, v6
	v_xor_b32_e32 v6, 2, v173
	s_add_u32 s4, s16, 0x18e00000
	v_cmp_lt_i32_e32 vcc, v6, v4
	s_addc_u32 s5, s17, 0
	v_readlane_b32 s53, v239, 60
	v_cndmask_b32_e32 v6, v173, v6, vcc
	v_lshlrev_b32_e32 v47, 2, v6
	v_xor_b32_e32 v6, 1, v173
	s_add_u32 s52, s16, 0x2a196100
	v_cmp_lt_i32_e32 vcc, v6, v4
	s_addc_u32 s53, s17, 0
	v_lshl_add_u64 v[28:29], s[54:55], 0, v[64:65]
	v_cndmask_b32_e32 v4, v173, v6, vcc
	v_lshl_add_u64 v[34:35], s[52:53], 0, v[64:65]
	v_lshl_add_u64 v[36:37], s[4:5], 0, v[64:65]
	v_lshlrev_b32_e32 v64, 1, v30
	v_ashrrev_i32_e32 v49, 13, v50
	s_mul_i32 s48, s48, 3
	v_lshlrev_b32_e32 v48, 2, v4
	v_lshl_add_u64 v[38:39], s[0:1], 0, v[64:65]
	v_add_u32_e32 v40, s58, v5
	s_mov_b64 s[54:55], 0
	v_readlane_b32 s2, v239, 9
	v_readlane_b32 s3, v239, 10
	v_readlane_b32 s6, v239, 13
	v_readlane_b32 s7, v239, 14
	v_readlane_b32 s8, v239, 15
	v_readlane_b32 s9, v239, 16
	v_readlane_b32 s10, v239, 17
	v_readlane_b32 s11, v239, 18
	v_readlane_b32 s14, v239, 21
	v_readlane_b32 s15, v239, 22
	v_cmp_gt_i32_e32 vcc, s84, v40
	s_nop 1
	v_cndmask_b32_e32 v234, 2, v49, vcc
	v_add_u32_e32 v234, s48, v234
	v_mul_lo_u32 v240, v234, s88
	v_ashrrev_i32_e32 v241, 31, v240
	v_lshl_add_u64 v[240:241], v[240:241], 2, v[36:37]
	v_add_co_u32_e32 v242, vcc, s83, v240
	s_nop 1
	v_addc_co_u32_e32 v243, vcc, 0, v241, vcc
	global_load_dwordx4 v[186:189], v[28:29], off
	global_load_dwordx4 v[190:193], v[240:241], off
	global_load_dwordx4 v[194:197], v[242:243], off
	global_load_dwordx4 v[198:201], v[28:29], off offset:1024
	global_load_dwordx4 v[202:205], v[240:241], off offset:1024
	global_load_dwordx4 v[206:209], v[242:243], off offset:1024
	global_load_dwordx4 v[210:213], v[28:29], off offset:2048
	global_load_dwordx4 v[214:217], v[240:241], off offset:2048
	global_load_dwordx4 v[218:221], v[242:243], off offset:2048
	global_load_dwordx4 v[222:225], v[28:29], off offset:3072
	global_load_dwordx4 v[226:229], v[240:241], off offset:3072
	global_load_dwordx4 v[230:233], v[242:243], off offset:3072
	s_waitcnt vmcnt(0)
.LBB0_171:
	s_waitcnt vmcnt(0)
	v_mov_b64_e32 v[22:23], v[2:3]
	v_mov_b64_e32 v[26:27], v[10:11]
	v_mov_b64_e32 v[54:55], v[14:15]
	v_cmp_gt_i32_e32 vcc, s84, v40
	v_mov_b64_e32 v[20:21], v[0:1]
	v_mov_b64_e32 v[24:25], v[8:9]
	v_mov_b64_e32 v[52:53], v[12:13]
	v_lshl_add_u64 v[0:1], v[32:33], 0, s[54:55]
	v_cndmask_b32_e32 v7, 2, v49, vcc
	v_ashrrev_i32_e32 v41, 31, v40
	v_add_co_u32_e32 v6, vcc, 0x1000, v0
	v_mov_b32_e32 v10, v53
	v_mov_b32_e32 v11, v25
	v_add_u32_e32 v0, s48, v7
	v_mov_b32_e32 v5, v17
	v_mov_b32_e32 v8, v52
	v_mov_b32_e32 v9, v24
	v_mov_b32_e32 v4, v21
	v_lshlrev_b64 v[12:13], 12, v[40:41]
	v_pk_mul_f32 v[10:11], v[10:11], v[10:11]
	v_mul_lo_u32 v76, v0, s88
	v_mov_b32_e32 v3, v16
	v_mov_b32_e32 v58, v54
	v_mov_b32_e32 v59, v26
	v_mov_b32_e32 v2, v20
	v_lshlrev_b64 v[14:15], 11, v[40:41]
	v_pk_mul_f32 v[4:5], v[4:5], v[4:5]
	v_lshl_add_u64 v[74:75], v[34:35], 0, v[12:13]
	v_addc_co_u32_e32 v7, vcc, 0, v1, vcc
	v_pk_fma_f32 v[78:79], v[8:9], v[8:9], v[10:11]
	v_ashrrev_i32_e32 v77, 31, v76
	v_mov_b32_e32 v68, v52
	v_mov_b32_e32 v69, v54
	v_lshl_add_u64 v[42:43], v[38:39], 0, v[14:15]
	v_pk_fma_f32 v[80:81], v[2:3], v[2:3], v[4:5]
	global_load_dwordx4 v[12:15], v[6:7], off
	global_load_dwordx4 v[8:11], v[6:7], off offset:1024
	global_load_dwordx4 v[0:3], v[6:7], off offset:2048
	s_nop 0
	global_load_dwordx4 v[4:7], v[6:7], off offset:3072
	s_nop 0
	global_store_dwordx4 v[74:75], v[52:55], off
	global_store_dwordx4 v[74:75], v[24:27], off offset:1024
	global_store_dwordx4 v[74:75], v[20:23], off offset:2048
	global_store_dwordx4 v[74:75], v[16:19], off offset:3072
	v_mov_b32_e32 v54, v53
	v_pk_fma_f32 v[52:53], v[58:59], v[58:59], v[78:79]
	v_lshl_add_u64 v[78:79], v[76:77], 2, v[36:37]
	v_mov_b32_e32 v57, v18
	v_mov_b32_e32 v56, v22
	v_add_co_u32_e32 v82, vcc, s83, v78
	v_mov_b32_e32 v61, v19
	v_mov_b32_e32 v62, v55
	v_mov_b32_e32 v63, v27
	v_mov_b32_e32 v60, v23
	v_pk_fma_f32 v[74:75], v[56:57], v[56:57], v[80:81]
	v_mov_b64_e32 v[56:57], v[186:187]
	v_mov_b64_e32 v[58:59], v[188:189]
	v_addc_co_u32_e32 v83, vcc, 0, v79, vcc
	v_pk_fma_f32 v[52:53], v[62:63], v[62:63], v[52:53]
	v_pk_fma_f32 v[80:81], v[60:61], v[60:61], v[74:75]
	v_mov_b64_e32 v[60:61], v[190:191]
	v_mov_b64_e32 v[62:63], v[192:193]
	v_mov_b64_e32 v[74:75], v[194:195]
	v_mov_b64_e32 v[76:77], v[196:197]
	v_add_f32_e32 v41, v52, v53
	v_add_f32_e32 v41, v41, v80
	v_add_f32_e32 v41, v41, v81
	ds_bpermute_b32 v51, v31, v41
	s_add_u32 s54, s54, 0x1000
	s_addc_u32 s55, s55, 0
	v_add_u32_e32 v40, 1, v40
	s_cmpk_lg_u32 s54, 0xf000
	s_waitcnt lgkmcnt(0)
; __device__ __forceinline__ unsigned pack2(float a, float b) { return (unsigned)f2bf(a) | ((unsigned)f2bf(b) << 16); }
; __device__ __forceinline__ void norm_job(const Params& p, int l, int job, bool from_x) {
;     ...
;     float ss = 0.f;
; #pragma unroll
;     for (int q = 0; q < 4; ++q) {
;       ss += xv[q].x * xv[q].x + xv[q].y * xv[q].y + xv[q].z * xv[q].z + xv[q].w * xv[q].w;
;     }
;     ss = wave_sum(ss);
;     float rstd = rsqrtf(ss * (1.f / 1024.f) + EPSF);
;     if (from_x) {
;       float* dstr = (float*)(ws + OFF_XNEW) + (size_t)row * 1024;
; #pragma unroll
;       for (int q = 0; q < 4; ++q) *(float4*)&dstr[lane * 4 + 256 * q] = xv[q];
;     } else if (row < MLAT) {
;       float* dstr = p.out + (size_t)row * 1024;
; #pragma unroll
;       for (int q = 0; q < 4; ++q) *(float4*)&dstr[lane * 4 + 256 * q] = xv[q];
;     }
; #pragma unroll
;     for (int q = 0; q < 4; ++q) {
;       int col = lane * 4 + 256 * q;
;       float4 w = *(const float4*)&nw[col];
;       float4 sh = *(const float4*)&mods[col];
;       float4 sc = *(const float4*)&mods[1024 + col];
;       float o0 = xv[q].x * rstd * w.x * (1.f + sc.x) + sh.x;
;       float o1 = xv[q].y * rstd * w.y * (1.f + sc.y) + sh.y;
;       float o2 = xv[q].z * rstd * w.z * (1.f + sc.z) + sh.z;
;       float o3 = xv[q].w * rstd * w.w * (1.f + sc.w) + sh.w;
;       uint2 o; o.x = pack2(o0, o1); o.y = pack2(o2, o3);
;       *(uint2*)&HL[(size_t)row * 1024 + col] = o;
;     }
	v_add_f32_e32 v41, v41, v51
	ds_bpermute_b32 v51, v44, v41
	s_waitcnt lgkmcnt(0)
	v_add_f32_e32 v41, v41, v51
	ds_bpermute_b32 v51, v45, v41
	s_waitcnt lgkmcnt(0)
	v_add_f32_e32 v41, v41, v51
	ds_bpermute_b32 v51, v46, v41
	s_waitcnt lgkmcnt(0)
	v_add_f32_e32 v41, v41, v51
	ds_bpermute_b32 v51, v47, v41
	s_waitcnt lgkmcnt(0)
	v_add_f32_e32 v41, v41, v51
	ds_bpermute_b32 v51, v48, v41
	s_waitcnt lgkmcnt(0)
	v_add_f32_e32 v41, v41, v51
	v_fmamk_f32 v41, v41, 0x3a800000, v70
	v_mul_f32_e32 v51, 0x4b800000, v41
	v_cmp_gt_f32_e32 vcc, s89, v41
	s_nop 1
	v_cndmask_b32_e32 v41, v41, v51, vcc
	v_rsq_f32_e32 v41, v41
	s_nop 0
	v_mul_f32_e32 v51, 0x45800000, v41
	v_cndmask_b32_e32 v64, v41, v51, vcc
	v_pk_mul_f32 v[52:53], v[68:69], v[64:65] op_sel_hi:[1,0]
	v_pk_mul_f32 v[54:55], v[54:55], v[64:65] op_sel_hi:[1,0]
	s_waitcnt vmcnt(0)
	v_mov_b32_e32 v69, v58
	v_mov_b32_e32 v58, v57
	v_mov_b32_e32 v68, v56
	v_pk_mul_f32 v[54:55], v[58:59], v[54:55]
	v_pk_mul_f32 v[52:53], v[68:69], v[52:53]
	v_mov_b32_e32 v56, v60
	v_mov_b32_e32 v58, v74
	v_mov_b32_e32 v59, v76
	v_mov_b32_e32 v76, v75
	v_mov_b32_e32 v57, v62
	v_mov_b32_e32 v62, v61
	v_pk_add_f32 v[58:59], v[58:59], 1.0 op_sel_hi:[1,0]
	v_pk_add_f32 v[60:61], v[76:77], 1.0 op_sel_hi:[1,0]
	v_pk_fma_f32 v[52:53], v[52:53], v[58:59], v[56:57]
	v_pk_fma_f32 v[54:55], v[54:55], v[60:61], v[62:63]
	v_and_b32_sdwa v41, v53, v73 dst_sel:DWORD dst_unused:UNUSED_PAD src0_sel:WORD_1 src1_sel:DWORD
	v_and_b32_sdwa v51, v52, v73 dst_sel:DWORD dst_unused:UNUSED_PAD src0_sel:WORD_1 src1_sel:DWORD
	v_and_b32_sdwa v56, v55, v73 dst_sel:DWORD dst_unused:UNUSED_PAD src0_sel:WORD_1 src1_sel:DWORD
	v_and_b32_sdwa v57, v54, v73 dst_sel:DWORD dst_unused:UNUSED_PAD src0_sel:WORD_1 src1_sel:DWORD
	v_add3_u32 v51, v52, v51, s87
	v_add3_u32 v41, v53, v41, s87
	v_add3_u32 v52, v55, v56, s87
	v_add3_u32 v53, v54, v57, s87
	v_and_b32_e32 v52, 0xffff0000, v52
	v_and_b32_e32 v54, 0xffff0000, v53
	v_or_b32_sdwa v53, v52, v41 dst_sel:DWORD dst_unused:UNUSED_PAD src0_sel:DWORD src1_sel:WORD_1
	v_or_b32_sdwa v52, v54, v51 dst_sel:DWORD dst_unused:UNUSED_PAD src0_sel:DWORD src1_sel:WORD_1
	global_store_dwordx2 v[42:43], v[52:53], off
	v_mov_b64_e32 v[52:53], v[198:199]
	v_mov_b64_e32 v[54:55], v[200:201]
	s_nop 0
	v_mov_b64_e32 v[56:57], v[206:207]
	v_mov_b64_e32 v[58:59], v[208:209]
	v_mov_b64_e32 v[60:61], v[202:203]
	v_mov_b64_e32 v[62:63], v[204:205]
	v_mov_b32_e32 v68, v24
	v_mov_b32_e32 v69, v26
	v_mov_b32_e32 v26, v25
	v_pk_mul_f32 v[24:25], v[68:69], v[64:65] op_sel_hi:[1,0]
	v_pk_mul_f32 v[26:27], v[26:27], v[64:65] op_sel_hi:[1,0]
	v_mov_b32_e32 v69, v54
	s_waitcnt lgkmcnt(0)
	v_mov_b32_e32 v75, v58
	v_mov_b32_e32 v54, v53
	v_mov_b32_e32 v58, v57
	v_mov_b32_e32 v68, v52
	v_mov_b32_e32 v74, v56
	v_mov_b32_e32 v77, v62
	v_mov_b32_e32 v62, v61
	v_pk_mul_f32 v[26:27], v[26:27], v[54:55]
	v_pk_add_f32 v[54:55], v[58:59], 1.0 op_sel_hi:[1,0]
	v_mov_b32_e32 v76, v60
	v_pk_mul_f32 v[24:25], v[24:25], v[68:69]
	v_pk_add_f32 v[52:53], v[74:75], 1.0 op_sel_hi:[1,0]
	v_pk_fma_f32 v[26:27], v[26:27], v[54:55], v[62:63]
	v_pk_fma_f32 v[24:25], v[24:25], v[52:53], v[76:77]
	v_and_b32_sdwa v52, v27, v73 dst_sel:DWORD dst_unused:UNUSED_PAD src0_sel:WORD_1 src1_sel:DWORD
	v_and_b32_sdwa v53, v26, v73 dst_sel:DWORD dst_unused:UNUSED_PAD src0_sel:WORD_1 src1_sel:DWORD
	v_and_b32_sdwa v41, v25, v73 dst_sel:DWORD dst_unused:UNUSED_PAD src0_sel:WORD_1 src1_sel:DWORD
	v_and_b32_sdwa v51, v24, v73 dst_sel:DWORD dst_unused:UNUSED_PAD src0_sel:WORD_1 src1_sel:DWORD
	v_add3_u32 v27, v27, v52, s87
	v_add3_u32 v26, v26, v53, s87
	v_add3_u32 v24, v24, v51, s87
	v_add3_u32 v25, v25, v41, s87
	v_and_b32_e32 v27, 0xffff0000, v27
	v_and_b32_e32 v26, 0xffff0000, v26
	v_or_b32_sdwa v25, v27, v25 dst_sel:DWORD dst_unused:UNUSED_PAD src0_sel:DWORD src1_sel:WORD_1
	v_or_b32_sdwa v24, v26, v24 dst_sel:DWORD dst_unused:UNUSED_PAD src0_sel:DWORD src1_sel:WORD_1
	global_store_dwordx2 v[42:43], v[24:25], off offset:512
	v_mov_b64_e32 v[24:25], v[210:211]
	v_mov_b64_e32 v[26:27], v[212:213]
	s_nop 0
	v_mov_b64_e32 v[52:53], v[218:219]
	v_mov_b64_e32 v[54:55], v[220:221]
	v_mov_b64_e32 v[56:57], v[214:215]
	v_mov_b64_e32 v[58:59], v[216:217]
	v_mov_b32_e32 v60, v20
	v_mov_b32_e32 v61, v22
	v_mov_b32_e32 v22, v21
	v_pk_mul_f32 v[20:21], v[60:61], v[64:65] op_sel_hi:[1,0]
	v_pk_mul_f32 v[22:23], v[22:23], v[64:65] op_sel_hi:[1,0]
	v_mov_b32_e32 v61, v26
	s_waitcnt lgkmcnt(0)
	v_mov_b32_e32 v63, v54
	v_mov_b32_e32 v26, v25
	v_mov_b32_e32 v54, v53
	v_mov_b32_e32 v60, v24
	v_mov_b32_e32 v62, v52
	v_mov_b32_e32 v69, v58
	v_mov_b32_e32 v58, v57
	v_pk_mul_f32 v[22:23], v[22:23], v[26:27]
	v_pk_add_f32 v[26:27], v[54:55], 1.0 op_sel_hi:[1,0]
	v_mov_b32_e32 v68, v56
	v_pk_mul_f32 v[20:21], v[20:21], v[60:61]
	v_pk_add_f32 v[24:25], v[62:63], 1.0 op_sel_hi:[1,0]
	v_pk_fma_f32 v[22:23], v[22:23], v[26:27], v[58:59]
	v_pk_fma_f32 v[20:21], v[20:21], v[24:25], v[68:69]
	v_and_b32_sdwa v26, v23, v73 dst_sel:DWORD dst_unused:UNUSED_PAD src0_sel:WORD_1 src1_sel:DWORD
	v_and_b32_sdwa v27, v22, v73 dst_sel:DWORD dst_unused:UNUSED_PAD src0_sel:WORD_1 src1_sel:DWORD
	v_and_b32_sdwa v24, v21, v73 dst_sel:DWORD dst_unused:UNUSED_PAD src0_sel:WORD_1 src1_sel:DWORD
	v_and_b32_sdwa v25, v20, v73 dst_sel:DWORD dst_unused:UNUSED_PAD src0_sel:WORD_1 src1_sel:DWORD
	v_add3_u32 v23, v23, v26, s87
	v_add3_u32 v22, v22, v27, s87
	v_add3_u32 v20, v20, v25, s87
	v_add3_u32 v21, v21, v24, s87
	v_and_b32_e32 v23, 0xffff0000, v23
	v_and_b32_e32 v22, 0xffff0000, v22
	v_or_b32_sdwa v21, v23, v21 dst_sel:DWORD dst_unused:UNUSED_PAD src0_sel:DWORD src1_sel:WORD_1
	v_or_b32_sdwa v20, v22, v20 dst_sel:DWORD dst_unused:UNUSED_PAD src0_sel:DWORD src1_sel:WORD_1
	global_store_dwordx2 v[42:43], v[20:21], off offset:1024
	v_mov_b64_e32 v[20:21], v[222:223]
	v_mov_b64_e32 v[22:23], v[224:225]
	s_nop 0
	v_mov_b64_e32 v[24:25], v[230:231]
	v_mov_b64_e32 v[26:27], v[232:233]
	v_mov_b64_e32 v[52:53], v[226:227]
	v_mov_b64_e32 v[54:55], v[228:229]
	v_mov_b32_e32 v57, v18
	v_mov_b32_e32 v18, v17
	v_mov_b32_e32 v56, v16
	v_pk_mul_f32 v[58:59], v[18:19], v[64:65] op_sel_hi:[1,0]
	v_pk_mul_f32 v[56:57], v[56:57], v[64:65] op_sel_hi:[1,0]
	v_mov_b64_e32 v[18:19], v[6:7]
	v_mov_b64_e32 v[16:17], v[4:5]
	v_mov_b32_e32 v61, v22
	s_waitcnt lgkmcnt(0)
; __device__ __forceinline__ unsigned pack2(float a, float b) { return (unsigned)f2bf(a) | ((unsigned)f2bf(b) << 16); }
; __device__ __forceinline__ void norm_job(const Params& p, int l, int job, bool from_x) {
;     ...
;   for (int i = 0; i < 16; ++i) {
;     int row = rowbase0 + i;
;     int v = row < MLAT ? (row >> 13) : 2;
;     const float* mods = (const float*)(ws + OFF_MODS) + (l * 3 + v) * 6144;
;     float4 xv[4];
;     xv[0] = nx0; xv[1] = nx1; xv[2] = nx2; xv[3] = nx3;
;     if (i + 1 < 16) {
;       const float* sn = src0 + (size_t)(i + 1) * 1024;
;       nx0 = *(const float4*)&sn[lane * 4]; nx1 = *(const float4*)&sn[lane * 4 + 256];
;       nx2 = *(const float4*)&sn[lane * 4 + 512]; nx3 = *(const float4*)&sn[lane * 4 + 768];
;     }
;     float ss = 0.f;
; #pragma unroll
;     for (int q = 0; q < 4; ++q) {
;       ss += xv[q].x * xv[q].x + xv[q].y * xv[q].y + xv[q].z * xv[q].z + xv[q].w * xv[q].w;
;     }
;     ss = wave_sum(ss);
;     float rstd = rsqrtf(ss * (1.f / 1024.f) + EPSF);
;     if (from_x) {
;       float* dstr = (float*)(ws + OFF_XNEW) + (size_t)row * 1024;
; #pragma unroll
;       for (int q = 0; q < 4; ++q) *(float4*)&dstr[lane * 4 + 256 * q] = xv[q];
;     } else if (row < MLAT) {
;       float* dstr = p.out + (size_t)row * 1024;
; #pragma unroll
;       for (int q = 0; q < 4; ++q) *(float4*)&dstr[lane * 4 + 256 * q] = xv[q];
;     }
; #pragma unroll
;     for (int q = 0; q < 4; ++q) {
;       int col = lane * 4 + 256 * q;
;       float4 w = *(const float4*)&nw[col];
;       float4 sh = *(const float4*)&mods[col];
;       float4 sc = *(const float4*)&mods[1024 + col];
;       float o0 = xv[q].x * rstd * w.x * (1.f + sc.x) + sh.x;
;       float o1 = xv[q].y * rstd * w.y * (1.f + sc.y) + sh.y;
;       float o2 = xv[q].z * rstd * w.z * (1.f + sc.z) + sh.z;
;       float o3 = xv[q].w * rstd * w.w * (1.f + sc.w) + sh.w;
;       uint2 o; o.x = pack2(o0, o1); o.y = pack2(o2, o3);
;       *(uint2*)&HL[(size_t)row * 1024 + col] = o;
;     }
	v_mov_b32_e32 v63, v26
	v_mov_b32_e32 v22, v21
	v_mov_b32_e32 v26, v25
	v_mov_b32_e32 v60, v20
	v_mov_b32_e32 v62, v24
	v_mov_b32_e32 v69, v54
	v_mov_b32_e32 v54, v53
	v_pk_mul_f32 v[22:23], v[58:59], v[22:23]
	v_pk_add_f32 v[26:27], v[26:27], 1.0 op_sel_hi:[1,0]
	v_mov_b32_e32 v68, v52
	v_pk_mul_f32 v[20:21], v[56:57], v[60:61]
	v_pk_add_f32 v[24:25], v[62:63], 1.0 op_sel_hi:[1,0]
	v_pk_fma_f32 v[22:23], v[22:23], v[26:27], v[54:55]
	v_pk_fma_f32 v[20:21], v[20:21], v[24:25], v[68:69]
	v_and_b32_sdwa v26, v23, v73 dst_sel:DWORD dst_unused:UNUSED_PAD src0_sel:WORD_1 src1_sel:DWORD
	v_and_b32_sdwa v27, v22, v73 dst_sel:DWORD dst_unused:UNUSED_PAD src0_sel:WORD_1 src1_sel:DWORD
	v_and_b32_sdwa v24, v21, v73 dst_sel:DWORD dst_unused:UNUSED_PAD src0_sel:WORD_1 src1_sel:DWORD
	v_and_b32_sdwa v25, v20, v73 dst_sel:DWORD dst_unused:UNUSED_PAD src0_sel:WORD_1 src1_sel:DWORD
	v_add3_u32 v23, v23, v26, s87
	v_add3_u32 v22, v22, v27, s87
	v_add3_u32 v20, v20, v25, s87
	v_add3_u32 v21, v21, v24, s87
	v_and_b32_e32 v23, 0xffff0000, v23
	v_and_b32_e32 v22, 0xffff0000, v22
	v_or_b32_sdwa v21, v23, v21 dst_sel:DWORD dst_unused:UNUSED_PAD src0_sel:DWORD src1_sel:WORD_1
	v_or_b32_sdwa v20, v22, v20 dst_sel:DWORD dst_unused:UNUSED_PAD src0_sel:DWORD src1_sel:WORD_1
	global_store_dwordx2 v[42:43], v[20:21], off offset:1536
	s_cbranch_scc1 .LBB0_171
	s_waitcnt vmcnt(0)
	v_or_b32_e32 v26, 15, v50
	v_ashrrev_i32_e32 v27, 31, v26
	v_lshlrev_b64 v[16:17], 12, v[26:27]
	v_lshl_add_u64 v[16:17], s[52:53], 0, v[16:17]
	v_lshlrev_b32_e32 v64, 2, v30
	v_lshl_add_u64 v[16:17], v[16:17], 0, v[64:65]
	v_cmp_gt_i32_e32 vcc, s84, v26
	global_store_dwordx4 v[16:17], v[12:15], off
	global_store_dwordx4 v[16:17], v[8:11], off offset:1024
	global_store_dwordx4 v[16:17], v[0:3], off offset:2048
	global_store_dwordx4 v[16:17], v[4:7], off offset:3072
	v_cndmask_b32_e32 v16, 2, v49, vcc
	v_add_u32_e32 v16, s48, v16
	v_mul_lo_u32 v16, v16, s88
	v_ashrrev_i32_e32 v17, 31, v16
	v_lshl_add_u64 v[16:17], v[16:17], 2, s[4:5]
	v_lshl_add_u64 v[16:17], v[16:17], 0, v[64:65]
	v_add_co_u32_e32 v40, vcc, s83, v16
	v_mov_b64_e32 v[18:19], v[186:187]
	v_mov_b64_e32 v[20:21], v[188:189]
	s_nop 0
	v_addc_co_u32_e32 v41, vcc, 0, v17, vcc
	v_mov_b64_e32 v[32:33], v[194:195]
	v_mov_b64_e32 v[34:35], v[196:197]
	v_mov_b64_e32 v[22:23], v[190:191]
	v_mov_b64_e32 v[24:25], v[192:193]
	v_mov_b32_e32 v38, v13
	v_mov_b32_e32 v39, v9
	v_mov_b32_e32 v36, v12
	v_mov_b32_e32 v37, v8
	v_pk_mul_f32 v[38:39], v[38:39], v[38:39]
	v_mov_b32_e32 v42, v1
	v_pk_fma_f32 v[36:37], v[36:37], v[36:37], v[38:39]
	v_mov_b32_e32 v38, v14
	v_mov_b32_e32 v39, v10
	v_pk_fma_f32 v[36:37], v[38:39], v[38:39], v[36:37]
	v_mov_b32_e32 v38, v15
	v_mov_b32_e32 v39, v11
	v_mov_b32_e32 v43, v5
	v_pk_fma_f32 v[36:37], v[38:39], v[38:39], v[36:37]
	v_mov_b32_e32 v38, v0
	v_mov_b32_e32 v39, v4
	v_pk_mul_f32 v[42:43], v[42:43], v[42:43]
	v_add_f32_e32 v36, v36, v37
	v_pk_fma_f32 v[38:39], v[38:39], v[38:39], v[42:43]
	v_mov_b32_e32 v42, v2
	v_mov_b32_e32 v43, v6
	v_pk_fma_f32 v[38:39], v[42:43], v[42:43], v[38:39]
	v_mov_b32_e32 v42, v3
	v_mov_b32_e32 v43, v7
	v_pk_fma_f32 v[38:39], v[42:43], v[42:43], v[38:39]
	v_mov_b32_e32 v37, v14
	v_add_f32_e32 v36, v36, v38
	v_add_f32_e32 v36, v36, v39
	ds_bpermute_b32 v31, v31, v36
	v_lshlrev_b32_e32 v64, 1, v30
	v_lshlrev_b64 v[26:27], 11, v[26:27]
	v_lshl_add_u64 v[26:27], s[0:1], 0, v[26:27]
	v_lshl_add_u64 v[26:27], v[26:27], 0, v[64:65]
	s_waitcnt lgkmcnt(0)
	v_add_f32_e32 v31, v36, v31
	ds_bpermute_b32 v36, v44, v31
	s_waitcnt lgkmcnt(0)
	v_add_f32_e32 v31, v31, v36
	ds_bpermute_b32 v36, v45, v31
	s_waitcnt lgkmcnt(0)
	v_add_f32_e32 v31, v31, v36
	ds_bpermute_b32 v36, v46, v31
	s_waitcnt lgkmcnt(0)
	v_add_f32_e32 v31, v31, v36
	ds_bpermute_b32 v36, v47, v31
	s_waitcnt lgkmcnt(0)
	v_add_f32_e32 v31, v31, v36
	ds_bpermute_b32 v38, v48, v31
	v_mov_b32_e32 v36, v12
	s_waitcnt lgkmcnt(0)
	v_add_f32_e32 v12, v31, v38
	v_fmamk_f32 v12, v12, 0x3a800000, v70
	v_mul_f32_e32 v14, 0x4b800000, v12
	v_cmp_gt_f32_e32 vcc, s89, v12
	s_nop 1
	v_cndmask_b32_e32 v12, v12, v14, vcc
	v_rsq_f32_e32 v12, v12
	v_mov_b32_e32 v14, v13
	v_mul_f32_e32 v13, 0x45800000, v12
	v_cndmask_b32_e32 v30, v12, v13, vcc
	v_pk_mul_f32 v[12:13], v[36:37], v[30:31] op_sel_hi:[1,0]
	v_pk_mul_f32 v[14:15], v[14:15], v[30:31] op_sel_hi:[1,0]
	v_mov_b32_e32 v37, v20
	v_mov_b32_e32 v20, v19
	v_mov_b32_e32 v36, v18
	v_pk_mul_f32 v[14:15], v[20:21], v[14:15]
	v_mov_b32_e32 v20, v32
	v_mov_b32_e32 v21, v34
	v_pk_mul_f32 v[12:13], v[36:37], v[12:13]
	v_mov_b32_e32 v18, v22
	v_mov_b32_e32 v19, v24
	v_mov_b32_e32 v34, v33
	v_pk_add_f32 v[20:21], v[20:21], 1.0 op_sel_hi:[1,0]
	v_mov_b32_e32 v24, v23
	v_pk_fma_f32 v[12:13], v[12:13], v[20:21], v[18:19]
	v_pk_add_f32 v[18:19], v[34:35], 1.0 op_sel_hi:[1,0]
	v_mov_b32_e32 v32, v8
	v_pk_fma_f32 v[14:15], v[14:15], v[18:19], v[24:25]
	v_and_b32_sdwa v18, v13, v73 dst_sel:DWORD dst_unused:UNUSED_PAD src0_sel:WORD_1 src1_sel:DWORD
	v_and_b32_sdwa v19, v12, v73 dst_sel:DWORD dst_unused:UNUSED_PAD src0_sel:WORD_1 src1_sel:DWORD
	v_add3_u32 v12, v12, v19, s87
	v_add3_u32 v13, v13, v18, s87
	v_and_b32_sdwa v18, v15, v73 dst_sel:DWORD dst_unused:UNUSED_PAD src0_sel:WORD_1 src1_sel:DWORD
	v_and_b32_sdwa v19, v14, v73 dst_sel:DWORD dst_unused:UNUSED_PAD src0_sel:WORD_1 src1_sel:DWORD
	v_add3_u32 v15, v15, v18, s87
	v_add3_u32 v14, v14, v19, s87
	v_and_b32_e32 v15, 0xffff0000, v15
	v_and_b32_e32 v14, 0xffff0000, v14
	v_or_b32_sdwa v13, v15, v13 dst_sel:DWORD dst_unused:UNUSED_PAD src0_sel:DWORD src1_sel:WORD_1
	v_or_b32_sdwa v12, v14, v12 dst_sel:DWORD dst_unused:UNUSED_PAD src0_sel:DWORD src1_sel:WORD_1
	global_store_dwordx2 v[26:27], v[12:13], off
	v_mov_b64_e32 v[12:13], v[198:199]
	v_mov_b64_e32 v[14:15], v[200:201]
	s_nop 0
	v_mov_b64_e32 v[18:19], v[206:207]
	v_mov_b64_e32 v[20:21], v[208:209]
	v_mov_b64_e32 v[22:23], v[202:203]
	v_mov_b64_e32 v[24:25], v[204:205]
	v_mov_b32_e32 v33, v10
	v_mov_b32_e32 v10, v9
	v_pk_mul_f32 v[8:9], v[32:33], v[30:31] op_sel_hi:[1,0]
	v_pk_mul_f32 v[10:11], v[10:11], v[30:31] op_sel_hi:[1,0]
	v_mov_b32_e32 v33, v14
	s_waitcnt lgkmcnt(0)
; __device__ __forceinline__ unsigned pack2(float a, float b) { return (unsigned)f2bf(a) | ((unsigned)f2bf(b) << 16); }
; __device__ __forceinline__ void norm_job(const Params& p, int l, int job, bool from_x) {
;     ...
; #pragma unroll
;     for (int q = 0; q < 4; ++q) {
;       int col = lane * 4 + 256 * q;
;       float4 w = *(const float4*)&nw[col];
;       float4 sh = *(const float4*)&mods[col];
;       float4 sc = *(const float4*)&mods[1024 + col];
;       float o0 = xv[q].x * rstd * w.x * (1.f + sc.x) + sh.x;
;       float o1 = xv[q].y * rstd * w.y * (1.f + sc.y) + sh.y;
;       float o2 = xv[q].z * rstd * w.z * (1.f + sc.z) + sh.z;
;       float o3 = xv[q].w * rstd * w.w * (1.f + sc.w) + sh.w;
;       uint2 o; o.x = pack2(o0, o1); o.y = pack2(o2, o3);
;       *(uint2*)&HL[(size_t)row * 1024 + col] = o;
;     }
	v_mov_b32_e32 v35, v20
	v_mov_b32_e32 v14, v13
	v_mov_b32_e32 v20, v19
	v_mov_b32_e32 v32, v12
	v_mov_b32_e32 v34, v18
	v_mov_b32_e32 v37, v24
	v_mov_b32_e32 v24, v23
	v_pk_mul_f32 v[10:11], v[10:11], v[14:15]
	v_pk_add_f32 v[14:15], v[20:21], 1.0 op_sel_hi:[1,0]
	v_mov_b32_e32 v36, v22
	v_pk_mul_f32 v[8:9], v[8:9], v[32:33]
	v_pk_add_f32 v[12:13], v[34:35], 1.0 op_sel_hi:[1,0]
	v_pk_fma_f32 v[10:11], v[10:11], v[14:15], v[24:25]
	v_pk_fma_f32 v[8:9], v[8:9], v[12:13], v[36:37]
	v_and_b32_sdwa v14, v11, v73 dst_sel:DWORD dst_unused:UNUSED_PAD src0_sel:WORD_1 src1_sel:DWORD
	v_and_b32_sdwa v15, v10, v73 dst_sel:DWORD dst_unused:UNUSED_PAD src0_sel:WORD_1 src1_sel:DWORD
	v_and_b32_sdwa v12, v9, v73 dst_sel:DWORD dst_unused:UNUSED_PAD src0_sel:WORD_1 src1_sel:DWORD
	v_and_b32_sdwa v13, v8, v73 dst_sel:DWORD dst_unused:UNUSED_PAD src0_sel:WORD_1 src1_sel:DWORD
	v_add3_u32 v11, v11, v14, s87
	v_add3_u32 v10, v10, v15, s87
	v_add3_u32 v8, v8, v13, s87
	v_add3_u32 v9, v9, v12, s87
	v_and_b32_e32 v11, 0xffff0000, v11
	v_and_b32_e32 v10, 0xffff0000, v10
	v_or_b32_sdwa v9, v11, v9 dst_sel:DWORD dst_unused:UNUSED_PAD src0_sel:DWORD src1_sel:WORD_1
	v_or_b32_sdwa v8, v10, v8 dst_sel:DWORD dst_unused:UNUSED_PAD src0_sel:DWORD src1_sel:WORD_1
	global_store_dwordx2 v[26:27], v[8:9], off offset:512
	v_mov_b64_e32 v[8:9], v[210:211]
	v_mov_b64_e32 v[10:11], v[212:213]
	s_nop 0
	v_mov_b64_e32 v[12:13], v[218:219]
	v_mov_b64_e32 v[14:15], v[220:221]
	v_mov_b64_e32 v[18:19], v[214:215]
	v_mov_b64_e32 v[20:21], v[216:217]
	v_mov_b32_e32 v22, v0
	v_mov_b32_e32 v23, v2
	v_mov_b32_e32 v2, v1
	v_pk_mul_f32 v[0:1], v[22:23], v[30:31] op_sel_hi:[1,0]
	v_pk_mul_f32 v[2:3], v[2:3], v[30:31] op_sel_hi:[1,0]
	v_mov_b32_e32 v23, v10
	s_waitcnt lgkmcnt(0)
	v_mov_b32_e32 v25, v14
	v_mov_b32_e32 v10, v9
	v_mov_b32_e32 v14, v13
	v_mov_b32_e32 v22, v8
	v_mov_b32_e32 v24, v12
	v_mov_b32_e32 v33, v20
	v_mov_b32_e32 v20, v19
	v_pk_mul_f32 v[2:3], v[2:3], v[10:11]
	v_pk_add_f32 v[10:11], v[14:15], 1.0 op_sel_hi:[1,0]
	v_mov_b32_e32 v32, v18
	v_pk_mul_f32 v[0:1], v[0:1], v[22:23]
	v_pk_add_f32 v[8:9], v[24:25], 1.0 op_sel_hi:[1,0]
	v_pk_fma_f32 v[2:3], v[2:3], v[10:11], v[20:21]
	v_pk_fma_f32 v[0:1], v[0:1], v[8:9], v[32:33]
	v_and_b32_sdwa v10, v3, v73 dst_sel:DWORD dst_unused:UNUSED_PAD src0_sel:WORD_1 src1_sel:DWORD
	v_and_b32_sdwa v11, v2, v73 dst_sel:DWORD dst_unused:UNUSED_PAD src0_sel:WORD_1 src1_sel:DWORD
	v_and_b32_sdwa v8, v1, v73 dst_sel:DWORD dst_unused:UNUSED_PAD src0_sel:WORD_1 src1_sel:DWORD
	v_and_b32_sdwa v9, v0, v73 dst_sel:DWORD dst_unused:UNUSED_PAD src0_sel:WORD_1 src1_sel:DWORD
	v_add3_u32 v3, v3, v10, s87
	v_add3_u32 v2, v2, v11, s87
	v_add3_u32 v0, v0, v9, s87
	v_add3_u32 v1, v1, v8, s87
	v_and_b32_e32 v3, 0xffff0000, v3
	v_and_b32_e32 v2, 0xffff0000, v2
	v_or_b32_sdwa v1, v3, v1 dst_sel:DWORD dst_unused:UNUSED_PAD src0_sel:DWORD src1_sel:WORD_1
	v_or_b32_sdwa v0, v2, v0 dst_sel:DWORD dst_unused:UNUSED_PAD src0_sel:DWORD src1_sel:WORD_1
	global_store_dwordx2 v[26:27], v[0:1], off offset:1024
	v_mov_b64_e32 v[0:1], v[222:223]
	v_mov_b64_e32 v[2:3], v[224:225]
	s_nop 0
	v_mov_b64_e32 v[8:9], v[230:231]
	v_mov_b64_e32 v[10:11], v[232:233]
	v_mov_b64_e32 v[12:13], v[226:227]
	v_mov_b64_e32 v[14:15], v[228:229]
	v_mov_b32_e32 v16, v4
	v_mov_b32_e32 v17, v6
	v_mov_b32_e32 v6, v5
	v_pk_mul_f32 v[4:5], v[16:17], v[30:31] op_sel_hi:[1,0]
	v_pk_mul_f32 v[6:7], v[6:7], v[30:31] op_sel_hi:[1,0]
	v_mov_b32_e32 v17, v2
	s_waitcnt lgkmcnt(0)
	v_mov_b32_e32 v19, v10
	v_mov_b32_e32 v2, v1
	v_mov_b32_e32 v10, v9
	v_mov_b32_e32 v16, v0
	v_mov_b32_e32 v18, v8
	v_mov_b32_e32 v21, v14
	v_mov_b32_e32 v14, v13
	v_pk_mul_f32 v[2:3], v[6:7], v[2:3]
	v_pk_add_f32 v[6:7], v[10:11], 1.0 op_sel_hi:[1,0]
	v_mov_b32_e32 v20, v12
	v_pk_mul_f32 v[0:1], v[4:5], v[16:17]
	v_pk_add_f32 v[4:5], v[18:19], 1.0 op_sel_hi:[1,0]
	v_pk_fma_f32 v[2:3], v[2:3], v[6:7], v[14:15]
	v_pk_fma_f32 v[0:1], v[0:1], v[4:5], v[20:21]
	v_and_b32_sdwa v6, v3, v73 dst_sel:DWORD dst_unused:UNUSED_PAD src0_sel:WORD_1 src1_sel:DWORD
	v_and_b32_sdwa v7, v2, v73 dst_sel:DWORD dst_unused:UNUSED_PAD src0_sel:WORD_1 src1_sel:DWORD
	v_and_b32_sdwa v4, v1, v73 dst_sel:DWORD dst_unused:UNUSED_PAD src0_sel:WORD_1 src1_sel:DWORD
	v_and_b32_sdwa v5, v0, v73 dst_sel:DWORD dst_unused:UNUSED_PAD src0_sel:WORD_1 src1_sel:DWORD
	v_add3_u32 v3, v3, v6, s87
	v_add3_u32 v2, v2, v7, s87
	v_add3_u32 v0, v0, v5, s87
	v_add3_u32 v1, v1, v4, s87
	v_and_b32_e32 v3, 0xffff0000, v3
	v_and_b32_e32 v2, 0xffff0000, v2
	v_or_b32_sdwa v1, v3, v1 dst_sel:DWORD dst_unused:UNUSED_PAD src0_sel:DWORD src1_sel:WORD_1
	v_or_b32_sdwa v0, v2, v0 dst_sel:DWORD dst_unused:UNUSED_PAD src0_sel:DWORD src1_sel:WORD_1
	global_store_dwordx2 v[26:27], v[0:1], off offset:1536
	s_branch .LBB0_156

; #define LAUNDER(v) asm volatile("" : "+s"(v))
; __device__ __forceinline__ int vtid() { int t = threadIdx.x; asm volatile("" : "+v"(t)); return t; }
; __device__ __forceinline__ void norm_job(const Params& p, int l, int job, bool from_x) {
;   const int tid = vtid(), lane = tid & 63, wid = tid >> 6;
;   char* ws = p.ws;
;   LAUNDER(ws); LAUNDER(l);
;   u16* HL = (u16*)(ws + OFF_HL);
;   const float* nw = p.norm1_w + l * 1024;
;   const int rowbase0 = job * 64 + wid * 16;
;   const float* src0;
;   if (from_x) src0 = rowbase0 < MLAT ? p.x + (size_t)rowbase0 * 1024 : p.ctx + (size_t)(rowbase0 - MLAT) * 1024;
;   else src0 = (const float*)(ws + OFF_XNEW) + (size_t)rowbase0 * 1024;
;   float4 nx0, nx1, nx2, nx3;
;   nx0 = *(const float4*)&src0[lane * 4]; nx1 = *(const float4*)&src0[lane * 4 + 256];
;   nx2 = *(const float4*)&src0[lane * 4 + 512]; nx3 = *(const float4*)&src0[lane * 4 + 768];
;     ...
;       float4 w = *(const float4*)&nw[col];
;       float4 sh = *(const float4*)&mods[col];
;       float4 sc = *(const float4*)&mods[1024 + col];
.LBB0_2022:
	v_mov_b32_e32 v8, v172
	s_mov_b64 s[8:9], s[58:59]
	v_ashrrev_i32_e32 v0, 2, v8
	v_and_b32_e32 v2, -16, v0
	v_lshl_add_u32 v38, s2, 6, v2
	v_ashrrev_i32_e32 v39, 31, v38
	v_lshlrev_b32_e32 v0, 2, v8
	v_lshlrev_b64 v[4:5], 12, v[38:39]
	v_and_b32_e32 v36, 0xfc, v0
	v_lshlrev_b32_e32 v0, 2, v36
	v_lshl_add_u64 v[4:5], s[8:9], 0, v[4:5]
	v_lshl_add_u64 v[4:5], v[4:5], 0, v[0:1]
	s_mov_b64 s[4:5], 0x2a196100
	s_mov_b32 s1, 0x2a196000
	s_mov_b32 s12, 1
	v_lshl_add_u64 v[6:7], v[4:5], 0, s[4:5]
	v_add_co_u32_e32 v4, vcc, s1, v4
	v_and_b32_e32 v3, 64, v173
	s_nop 0
	v_addc_co_u32_e32 v5, vcc, 0, v5, vcc
	s_waitcnt vmcnt(0)
	global_load_dwordx4 v[26:29], v[6:7], off offset:1024
	global_load_dwordx4 v[22:25], v[6:7], off offset:2048
	global_load_dwordx4 v[30:33], v[4:5], off offset:256
	global_load_dwordx4 v[18:21], v[6:7], off offset:3072
	v_add_u32_e32 v3, 64, v3
	v_xor_b32_e32 v4, 32, v173
	v_cmp_lt_i32_e32 vcc, v4, v3
	s_ashr_i32 s1, s0, 31
	s_add_u32 s4, s8, 0x1b2d6100
	v_cndmask_b32_e32 v4, v173, v4, vcc
	v_lshlrev_b32_e32 v39, 2, v4
	v_xor_b32_e32 v4, 16, v173
	v_cmp_lt_i32_e32 vcc, v4, v3
	s_addc_u32 s5, s9, 0
	s_lshl_b32 s6, s12, 10
	v_cndmask_b32_e32 v4, v173, v4, vcc
	v_lshlrev_b32_e32 v52, 2, v4
	v_xor_b32_e32 v4, 8, v173
	v_cmp_lt_i32_e32 vcc, v4, v3
	v_readlane_b32 s16, v239, 7
	s_ashr_i32 s7, s6, 31
	v_cndmask_b32_e32 v4, v173, v4, vcc
	v_lshlrev_b32_e32 v53, 2, v4
	v_xor_b32_e32 v4, 4, v173
	v_cmp_lt_i32_e32 vcc, v4, v3
	v_readlane_b32 s17, v239, 8
	v_readlane_b32 s18, v239, 9
	v_cndmask_b32_e32 v4, v173, v4, vcc
	v_readlane_b32 s19, v239, 10
	v_readlane_b32 s28, v239, 19
	v_readlane_b32 s29, v239, 20
	v_lshlrev_b32_e32 v54, 2, v4
	v_xor_b32_e32 v4, 2, v173
	s_lshl_b64 s[6:7], s[6:7], 2
	v_readlane_b32 s30, v239, 21
	v_readlane_b32 s31, v239, 22
	s_mov_b64 s[16:17], s[28:29]
	v_cmp_lt_i32_e32 vcc, v4, v3
	s_add_u32 s10, s16, s6
	s_addc_u32 s11, s17, s7
	v_cndmask_b32_e32 v4, v173, v4, vcc
	v_lshlrev_b32_e32 v55, 2, v4
	v_xor_b32_e32 v4, 1, v173
	s_add_u32 s6, s8, 0x18e00000
	v_cmp_lt_i32_e32 vcc, v4, v3
	s_addc_u32 s7, s9, 0
	v_lshl_add_u64 v[34:35], s[10:11], 0, v[0:1]
	v_cndmask_b32_e32 v3, v173, v4, vcc
	v_lshlrev_b32_e32 v56, 2, v3
	v_lshl_add_u64 v[40:41], s[56:57], 0, v[0:1]
	v_lshl_add_u64 v[42:43], s[6:7], 0, v[0:1]
	v_lshlrev_b32_e32 v0, 1, v36
	v_ashrrev_i32_e32 v3, 31, v2
	v_lshl_add_u64 v[44:45], s[4:5], 0, v[0:1]
	v_add_u32_e32 v0, s0, v2
	v_lshl_add_u64 v[2:3], s[0:1], 0, v[2:3]
	v_lshlrev_b64 v[2:3], 12, v[2:3]
	v_and_b32_e32 v4, 63, v8
	v_lshl_or_b32 v2, v4, 4, v2
	v_ashrrev_i32_e32 v37, 13, v38
	s_mul_i32 s12, s12, 3
	v_lshl_add_u64 v[46:47], s[8:9], 0, v[2:3]
	s_mov_b64 s[8:9], 0
	v_mov_b64_e32 v[48:49], v[0:1]
	v_readlane_b32 s20, v239, 11
	v_readlane_b32 s21, v239, 12
	v_readlane_b32 s22, v239, 13
	v_readlane_b32 s23, v239, 14
	v_readlane_b32 s24, v239, 15
	v_readlane_b32 s25, v239, 16
	v_readlane_b32 s26, v239, 17
	v_readlane_b32 s27, v239, 18
	s_mov_b64 s[18:19], s[30:31]
	v_cmp_gt_i32_e32 vcc, s91, v48
	s_nop 1
	v_cndmask_b32_e32 v211, 2, v37, vcc
	v_add_u32_e32 v211, s12, v211
	v_mov_b32_e32 v253, 0x1800
	v_mul_lo_u32 v252, v211, v253
	v_ashrrev_i32_e32 v253, 31, v252
	v_lshl_add_u64 v[252:253], v[252:253], 2, v[42:43]
	v_add_co_u32_e32 v254, vcc, 0x1000, v252
	s_nop 1
	v_addc_co_u32_e32 v255, vcc, 0, v253, vcc
	global_load_dwordx4 v[186:189], v[34:35], off
	global_load_dwordx4 v[190:193], v[252:253], off
	global_load_dwordx4 v[212:215], v[254:255], off
	global_load_dwordx4 v[216:219], v[34:35], off offset:1024
	global_load_dwordx4 v[220:223], v[252:253], off offset:1024
	global_load_dwordx4 v[224:227], v[254:255], off offset:1024
	global_load_dwordx4 v[228:231], v[34:35], off offset:2048
	global_load_dwordx4 v[232:235], v[252:253], off offset:2048
	global_load_dwordx4 v[240:243], v[254:255], off offset:2048
	global_load_dwordx4 v[244:247], v[34:35], off offset:3072
	global_load_dwordx4 v[248:251], v[252:253], off offset:3072
	global_load_dwordx4 v[252:255], v[254:255], off offset:3072
	s_waitcnt vmcnt(0)

; __device__ __forceinline__ unsigned pack2(float a, float b) { return (unsigned)f2bf(a) | ((unsigned)f2bf(b) << 16); }
; __device__ __forceinline__ void norm_job(const Params& p, int l, int job, bool from_x) {
;     ...
;     ss = wave_sum(ss);
;     float rstd = rsqrtf(ss * (1.f / 1024.f) + EPSF);
;     if (from_x) {
;       float* dstr = (float*)(ws + OFF_XNEW) + (size_t)row * 1024;
; #pragma unroll
;       for (int q = 0; q < 4; ++q) *(float4*)&dstr[lane * 4 + 256 * q] = xv[q];
;     } else if (row < MLAT) {
;       float* dstr = p.out + (size_t)row * 1024;
; #pragma unroll
;       for (int q = 0; q < 4; ++q) *(float4*)&dstr[lane * 4 + 256 * q] = xv[q];
;     }
; #pragma unroll
;     for (int q = 0; q < 4; ++q) {
;       int col = lane * 4 + 256 * q;
;       float4 w = *(const float4*)&nw[col];
;       float4 sh = *(const float4*)&mods[col];
;       float4 sc = *(const float4*)&mods[1024 + col];
;       float o0 = xv[q].x * rstd * w.x * (1.f + sc.x) + sh.x;
;       float o1 = xv[q].y * rstd * w.y * (1.f + sc.y) + sh.y;
;       float o2 = xv[q].z * rstd * w.z * (1.f + sc.z) + sh.z;
;       float o3 = xv[q].w * rstd * w.w * (1.f + sc.w) + sh.w;
;       uint2 o; o.x = pack2(o0, o1); o.y = pack2(o2, o3);
;       *(uint2*)&HL[(size_t)row * 1024 + col] = o;
;     }
.LBB0_2025:
	s_or_b64 exec, exec, s[10:11]
	v_cndmask_b32_e32 v58, 2, v37, vcc
	v_add_u32_e32 v58, s12, v58
	s_movk_i32 s1, 0x1800
	v_mul_lo_u32 v62, v58, s1
	v_ashrrev_i32_e32 v63, 31, v62
	v_lshl_add_u64 v[70:71], v[62:63], 2, v[42:43]
	s_movk_i32 s1, 0x1000
	v_add_co_u32_e32 v72, vcc, s1, v70
	v_mov_b64_e32 v[58:59], v[186:187]
	v_mov_b64_e32 v[60:61], v[188:189]
	s_nop 0
	v_addc_co_u32_e32 v73, vcc, 0, v71, vcc
	v_mov_b64_e32 v[62:63], v[190:191]
	v_mov_b64_e32 v[64:65], v[192:193]
	v_mov_b64_e32 v[66:67], v[212:213]
	v_mov_b64_e32 v[68:69], v[214:215]
	s_waitcnt lgkmcnt(0)
	v_add_f32_e32 v0, v0, v57
	v_fmamk_f32 v0, v0, 0x3a800000, v197
	v_mov_b32_e32 v74, v30
	v_mul_f32_e32 v30, 0x4b800000, v0
	v_cmp_gt_f32_e32 vcc, s92, v0
	v_lshlrev_b64 v[50:51], 11, v[50:51]
	v_mov_b32_e32 v75, v32
	v_cndmask_b32_e32 v0, v0, v30, vcc
	v_rsq_f32_e32 v0, v0
	v_mov_b32_e32 v32, v31
	v_lshl_add_u64 v[30:31], v[44:45], 0, v[50:51]
	s_add_u32 s8, s8, 0x1000
	v_mul_f32_e32 v50, 0x45800000, v0
	v_cndmask_b32_e32 v0, v0, v50, vcc
	v_pk_mul_f32 v[50:51], v[74:75], v[0:1] op_sel_hi:[1,0]
	v_pk_mul_f32 v[32:33], v[32:33], v[0:1] op_sel_hi:[1,0]
	s_addc_u32 s9, s9, 0
	s_cmpk_eq_u32 s8, 0xf000
	v_lshl_add_u64 v[48:49], v[48:49], 0, 1
	s_waitcnt vmcnt(0)
	v_mov_b32_e32 v75, v60
	v_mov_b32_e32 v60, v59
	v_pk_mul_f32 v[32:33], v[32:33], v[60:61]
	v_mov_b32_e32 v74, v58
	v_mov_b32_e32 v61, v68
	v_mov_b32_e32 v68, v67
	v_mov_b32_e32 v58, v62
	v_mov_b32_e32 v59, v64
	v_mov_b32_e32 v64, v63
	v_mov_b32_e32 v60, v66
	v_pk_add_f32 v[62:63], v[68:69], 1.0 op_sel_hi:[1,0]
	v_pk_mul_f32 v[50:51], v[50:51], v[74:75]
	v_pk_add_f32 v[60:61], v[60:61], 1.0 op_sel_hi:[1,0]
	v_pk_fma_f32 v[32:33], v[32:33], v[62:63], v[64:65]
	v_pk_fma_f32 v[50:51], v[50:51], v[60:61], v[58:59]
	v_and_b32_sdwa v59, v33, v198 dst_sel:DWORD dst_unused:UNUSED_PAD src0_sel:WORD_1 src1_sel:DWORD
	v_and_b32_sdwa v60, v32, v198 dst_sel:DWORD dst_unused:UNUSED_PAD src0_sel:WORD_1 src1_sel:DWORD
	v_and_b32_sdwa v57, v51, v198 dst_sel:DWORD dst_unused:UNUSED_PAD src0_sel:WORD_1 src1_sel:DWORD
	v_and_b32_sdwa v58, v50, v198 dst_sel:DWORD dst_unused:UNUSED_PAD src0_sel:WORD_1 src1_sel:DWORD
	v_add3_u32 v33, v33, v59, s33
	v_add3_u32 v32, v32, v60, s33
	v_add3_u32 v50, v50, v58, s33
	v_add3_u32 v51, v51, v57, s33
	v_and_b32_e32 v33, 0xffff0000, v33
	v_and_b32_e32 v32, 0xffff0000, v32
	v_or_b32_sdwa v33, v33, v51 dst_sel:DWORD dst_unused:UNUSED_PAD src0_sel:DWORD src1_sel:WORD_1
	v_or_b32_sdwa v32, v32, v50 dst_sel:DWORD dst_unused:UNUSED_PAD src0_sel:DWORD src1_sel:WORD_1
	global_store_dwordx2 v[30:31], v[32:33], off
	v_mov_b64_e32 v[58:59], v[216:217]
	v_mov_b64_e32 v[60:61], v[218:219]
	v_mov_b64_e32 v[62:63], v[224:225]
	v_mov_b64_e32 v[64:65], v[226:227]
	v_mov_b64_e32 v[66:67], v[220:221]
	v_mov_b64_e32 v[68:69], v[222:223]
	v_mov_b32_e32 v32, v26
	v_mov_b32_e32 v33, v28
	v_mov_b32_e32 v28, v27
	v_pk_mul_f32 v[26:27], v[32:33], v[0:1] op_sel_hi:[1,0]
	v_pk_mul_f32 v[28:29], v[28:29], v[0:1] op_sel_hi:[1,0]
	v_mov_b32_e32 v32, v58
	v_mov_b32_e32 v33, v60
	s_waitcnt lgkmcnt(0)
	v_mov_b32_e32 v50, v62
	v_mov_b32_e32 v51, v64
	v_mov_b32_e32 v60, v59
	v_mov_b32_e32 v64, v63
	v_mov_b32_e32 v75, v68
	v_mov_b32_e32 v68, v67
	v_pk_mul_f32 v[26:27], v[26:27], v[32:33]
	v_pk_add_f32 v[32:33], v[50:51], 1.0 op_sel_hi:[1,0]
	v_pk_mul_f32 v[28:29], v[28:29], v[60:61]
	v_pk_add_f32 v[50:51], v[64:65], 1.0 op_sel_hi:[1,0]
	v_mov_b32_e32 v74, v66
	v_pk_fma_f32 v[28:29], v[28:29], v[50:51], v[68:69]
	v_pk_fma_f32 v[26:27], v[26:27], v[32:33], v[74:75]
	v_and_b32_sdwa v50, v29, v198 dst_sel:DWORD dst_unused:UNUSED_PAD src0_sel:WORD_1 src1_sel:DWORD
	v_and_b32_sdwa v51, v28, v198 dst_sel:DWORD dst_unused:UNUSED_PAD src0_sel:WORD_1 src1_sel:DWORD
	v_and_b32_sdwa v32, v27, v198 dst_sel:DWORD dst_unused:UNUSED_PAD src0_sel:WORD_1 src1_sel:DWORD
	v_and_b32_sdwa v33, v26, v198 dst_sel:DWORD dst_unused:UNUSED_PAD src0_sel:WORD_1 src1_sel:DWORD
	v_add3_u32 v29, v29, v50, s33
	v_add3_u32 v28, v28, v51, s33
	v_add3_u32 v26, v26, v33, s33
	v_add3_u32 v27, v27, v32, s33
	v_and_b32_e32 v29, 0xffff0000, v29
	v_and_b32_e32 v28, 0xffff0000, v28
	v_or_b32_sdwa v27, v29, v27 dst_sel:DWORD dst_unused:UNUSED_PAD src0_sel:DWORD src1_sel:WORD_1
	v_or_b32_sdwa v26, v28, v26 dst_sel:DWORD dst_unused:UNUSED_PAD src0_sel:DWORD src1_sel:WORD_1
	global_store_dwordx2 v[30:31], v[26:27], off offset:512
	v_mov_b64_e32 v[26:27], v[228:229]
	v_mov_b64_e32 v[28:29], v[230:231]
	s_nop 0
	v_mov_b64_e32 v[58:59], v[240:241]
	v_mov_b64_e32 v[60:61], v[242:243]
	v_mov_b64_e32 v[62:63], v[232:233]
	v_mov_b64_e32 v[64:65], v[234:235]
	v_mov_b32_e32 v32, v22
	v_mov_b32_e32 v33, v24
	v_mov_b32_e32 v24, v23
	v_pk_mul_f32 v[22:23], v[32:33], v[0:1] op_sel_hi:[1,0]
	v_pk_mul_f32 v[24:25], v[24:25], v[0:1] op_sel_hi:[1,0]
	v_mov_b32_e32 v33, v28
	s_waitcnt lgkmcnt(0)
; __device__ __forceinline__ unsigned pack2(float a, float b) { return (unsigned)f2bf(a) | ((unsigned)f2bf(b) << 16); }
; __device__ __forceinline__ void norm_job(const Params& p, int l, int job, bool from_x) {
;     ...
;   for (int i = 0; i < 16; ++i) {
;     int row = rowbase0 + i;
;     int v = row < MLAT ? (row >> 13) : 2;
;     const float* mods = (const float*)(ws + OFF_MODS) + (l * 3 + v) * 6144;
;     float4 xv[4];
;     xv[0] = nx0; xv[1] = nx1; xv[2] = nx2; xv[3] = nx3;
;     if (i + 1 < 16) {
;       const float* sn = src0 + (size_t)(i + 1) * 1024;
;       nx0 = *(const float4*)&sn[lane * 4]; nx1 = *(const float4*)&sn[lane * 4 + 256];
;       nx2 = *(const float4*)&sn[lane * 4 + 512]; nx3 = *(const float4*)&sn[lane * 4 + 768];
;     }
;     ...
;     for (int q = 0; q < 4; ++q) {
;       int col = lane * 4 + 256 * q;
;       float4 w = *(const float4*)&nw[col];
;       float4 sh = *(const float4*)&mods[col];
;       float4 sc = *(const float4*)&mods[1024 + col];
;       float o0 = xv[q].x * rstd * w.x * (1.f + sc.x) + sh.x;
;       float o1 = xv[q].y * rstd * w.y * (1.f + sc.y) + sh.y;
;       float o2 = xv[q].z * rstd * w.z * (1.f + sc.z) + sh.z;
;       float o3 = xv[q].w * rstd * w.w * (1.f + sc.w) + sh.w;
;       uint2 o; o.x = pack2(o0, o1); o.y = pack2(o2, o3);
;       *(uint2*)&HL[(size_t)row * 1024 + col] = o;
;     }
	v_mov_b32_e32 v51, v60
	v_mov_b32_e32 v28, v27
	v_mov_b32_e32 v60, v59
	v_mov_b32_e32 v32, v26
	v_mov_b32_e32 v50, v58
	v_mov_b32_e32 v67, v64
	v_mov_b32_e32 v64, v63
	v_pk_mul_f32 v[24:25], v[24:25], v[28:29]
	v_pk_add_f32 v[28:29], v[60:61], 1.0 op_sel_hi:[1,0]
	v_mov_b32_e32 v66, v62
	v_pk_mul_f32 v[22:23], v[22:23], v[32:33]
	v_pk_add_f32 v[26:27], v[50:51], 1.0 op_sel_hi:[1,0]
	v_pk_fma_f32 v[24:25], v[24:25], v[28:29], v[64:65]
	v_pk_fma_f32 v[22:23], v[22:23], v[26:27], v[66:67]
	v_and_b32_sdwa v28, v25, v198 dst_sel:DWORD dst_unused:UNUSED_PAD src0_sel:WORD_1 src1_sel:DWORD
	v_and_b32_sdwa v29, v24, v198 dst_sel:DWORD dst_unused:UNUSED_PAD src0_sel:WORD_1 src1_sel:DWORD
	v_and_b32_sdwa v26, v23, v198 dst_sel:DWORD dst_unused:UNUSED_PAD src0_sel:WORD_1 src1_sel:DWORD
	v_and_b32_sdwa v27, v22, v198 dst_sel:DWORD dst_unused:UNUSED_PAD src0_sel:WORD_1 src1_sel:DWORD
	v_add3_u32 v25, v25, v28, s33
	v_add3_u32 v24, v24, v29, s33
	v_add3_u32 v22, v22, v27, s33
	v_add3_u32 v23, v23, v26, s33
	v_and_b32_e32 v25, 0xffff0000, v25
	v_and_b32_e32 v24, 0xffff0000, v24
	v_or_b32_sdwa v23, v25, v23 dst_sel:DWORD dst_unused:UNUSED_PAD src0_sel:DWORD src1_sel:WORD_1
	v_or_b32_sdwa v22, v24, v22 dst_sel:DWORD dst_unused:UNUSED_PAD src0_sel:DWORD src1_sel:WORD_1
	global_store_dwordx2 v[30:31], v[22:23], off offset:1024
	v_mov_b64_e32 v[22:23], v[244:245]
	v_mov_b64_e32 v[24:25], v[246:247]
	s_nop 0
	v_mov_b64_e32 v[26:27], v[252:253]
	v_mov_b64_e32 v[28:29], v[254:255]
	v_mov_b64_e32 v[58:59], v[248:249]
	v_mov_b64_e32 v[60:61], v[250:251]
	v_mov_b32_e32 v32, v18
	v_mov_b32_e32 v33, v20
	v_mov_b32_e32 v20, v19
	v_pk_mul_f32 v[18:19], v[32:33], v[0:1] op_sel_hi:[1,0]
	v_pk_mul_f32 v[20:21], v[20:21], v[0:1] op_sel_hi:[1,0]
	v_mov_b32_e32 v32, v22
	v_mov_b32_e32 v33, v24
	s_waitcnt lgkmcnt(0)
	v_mov_b32_e32 v50, v26
	v_mov_b32_e32 v51, v28
	v_mov_b32_e32 v24, v23
	v_mov_b32_e32 v28, v27
	v_mov_b32_e32 v62, v58
	v_mov_b32_e32 v63, v60
	v_mov_b32_e32 v60, v59
	v_pk_mul_f32 v[18:19], v[18:19], v[32:33]
	v_pk_add_f32 v[22:23], v[50:51], 1.0 op_sel_hi:[1,0]
	v_pk_mul_f32 v[20:21], v[20:21], v[24:25]
	v_pk_add_f32 v[24:25], v[28:29], 1.0 op_sel_hi:[1,0]
	v_pk_fma_f32 v[18:19], v[18:19], v[22:23], v[62:63]
	v_pk_fma_f32 v[20:21], v[20:21], v[24:25], v[60:61]
	v_and_b32_sdwa v0, v19, v198 dst_sel:DWORD dst_unused:UNUSED_PAD src0_sel:WORD_1 src1_sel:DWORD
	v_and_b32_sdwa v23, v21, v198 dst_sel:DWORD dst_unused:UNUSED_PAD src0_sel:WORD_1 src1_sel:DWORD
	v_and_b32_sdwa v24, v20, v198 dst_sel:DWORD dst_unused:UNUSED_PAD src0_sel:WORD_1 src1_sel:DWORD
	v_and_b32_sdwa v22, v18, v198 dst_sel:DWORD dst_unused:UNUSED_PAD src0_sel:WORD_1 src1_sel:DWORD
	v_add3_u32 v0, v19, v0, s33
	v_add3_u32 v19, v21, v23, s33
	v_add3_u32 v20, v20, v24, s33
	v_add3_u32 v18, v18, v22, s33
	v_and_b32_e32 v19, 0xffff0000, v19
	v_and_b32_e32 v20, 0xffff0000, v20
	v_or_b32_sdwa v19, v19, v0 dst_sel:DWORD dst_unused:UNUSED_PAD src0_sel:DWORD src1_sel:WORD_1
	v_or_b32_sdwa v18, v20, v18 dst_sel:DWORD dst_unused:UNUSED_PAD src0_sel:DWORD src1_sel:WORD_1
	global_store_dwordx2 v[30:31], v[18:19], off offset:1536
	s_cbranch_scc1 .LBB0_2027
	v_mov_b64_e32 v[32:33], v[16:17]
	v_mov_b64_e32 v[28:29], v[12:13]
	v_mov_b64_e32 v[24:25], v[8:9]
	v_mov_b64_e32 v[20:21], v[4:5]
	v_mov_b64_e32 v[30:31], v[14:15]
	v_mov_b64_e32 v[26:27], v[10:11]
	v_mov_b64_e32 v[22:23], v[6:7]
	v_mov_b64_e32 v[18:19], v[2:3]
	s_branch .LBB0_2023
